# attention loop trimmed: conditional vmcnt ladders replaced by one vmcnt(0) at the end of the first softmax segment, LDS-DMA with SGPR base addressing, 4 counted lgkmcnt waits per MFMA segment, 1-state
# speedup vs baseline: 1.0373x; 1.0199x over previous
; #define AT_BAR() do { __builtin_amdgcn_sched_barrier(0); asm volatile("s_waitcnt lgkmcnt(0)\n\ts_barrier" ::: "memory"); __builtin_amdgcn_sched_barrier(0); } while (0)
; #define AT_PIN_M() asm volatile("" : "+v"(p[0]), "+v"(p[1]), "+v"(o[0][0]), "+v"(o[0][1]), "+v"(o[1][0]), "+v"(o[1][1]))
; __device__ __forceinline__ void attn_phase(LAS unsigned char* lds, const bf16_t* Qb, const bf16_t* Kimg, const bf16_t* Vimg, bf16_t* AB, int bid, int G, int wave_k) {
;     ...
;         for (int t = 0; t < 256; ++t) {
;             AT_MSEG(b_cur, 0, (t > 0 ? b_prev : b_cur), 2);
;             AT_PIN_M();
;             AT_BAR();
;             AT_SM(t == 0);
;             AT_BAR();
;             const bool issued = (t + 2 < 256);
;             if (issued) AT_ISSUE(t + 2, b_prev);
.LBB0_963:
	s_mov_b32 s64, s16
	v_add_u32_e32 v160, s62, v236
	v_add_u32_e32 v128, s64, v236
	ds_read_b128 v[104:107], v160
	ds_read_b128 v[108:111], v160 offset:2048
	ds_read_b128 v[120:123], v160 offset:4096
	ds_read_b128 v[124:127], v160 offset:6144
	ds_read_b128 v[210:213], v160 offset:8192
	ds_read_b128 v[230:233], v160 offset:10240
	ds_read_b128 v[238:241], v128 offset:16384
	ds_read_b128 v[242:245], v128 offset:16896
	ds_read_b128 v[246:249], v128 offset:18432
	ds_read_b128 v[250:253], v128 offset:18944
	s_setprio 1
	s_waitcnt lgkmcnt(9)
	v_mfma_f32_32x32x16_bf16 v[144:159], v[104:107], v[162:165], v[64:79]
	v_mfma_f32_32x32x16_bf16 v[128:143], v[104:107], v[186:189], v[80:95]
	s_waitcnt lgkmcnt(7)
	v_mfma_f32_32x32x16_bf16 v[144:159], v[108:111], v[166:169], v[144:159]
	v_mfma_f32_32x32x16_bf16 v[128:143], v[108:111], v[190:193], v[128:143]
	v_mfma_f32_32x32x16_bf16 v[144:159], v[120:123], v[170:173], v[144:159]
	v_mfma_f32_32x32x16_bf16 v[128:143], v[120:123], v[194:197], v[128:143]
	s_waitcnt lgkmcnt(4)
	v_mfma_f32_32x32x16_bf16 v[144:159], v[124:127], v[174:177], v[144:159]
	v_mfma_f32_32x32x16_bf16 v[128:143], v[124:127], v[198:201], v[128:143]
	v_mfma_f32_32x32x16_bf16 v[144:159], v[210:213], v[178:181], v[144:159]
	v_mfma_f32_32x32x16_bf16 v[128:143], v[210:213], v[202:205], v[128:143]
	v_mfma_f32_32x32x16_bf16 v[144:159], v[230:233], v[182:185], v[144:159]
	v_mfma_f32_32x32x16_bf16 v[128:143], v[230:233], v[206:209], v[128:143]
	s_waitcnt lgkmcnt(0)
	v_mfma_f32_32x32x16_bf16 v[48:63], v[238:241], v[116:119], v[48:63]
	v_mfma_f32_32x32x16_bf16 v[32:47], v[242:245], v[116:119], v[32:47]
	v_mfma_f32_32x32x16_bf16 v[16:31], v[238:241], v[100:103], v[16:31]
	v_mfma_f32_32x32x16_bf16 v[0:15], v[242:245], v[100:103], v[0:15]
	v_mfma_f32_32x32x16_bf16 v[48:63], v[246:249], v[112:115], v[48:63]
	v_mfma_f32_32x32x16_bf16 v[32:47], v[250:253], v[112:115], v[32:47]
	v_mfma_f32_32x32x16_bf16 v[16:31], v[246:249], v[96:99], v[16:31]
	v_mfma_f32_32x32x16_bf16 v[0:15], v[250:253], v[96:99], v[0:15]
	s_setprio 0
	s_waitcnt lgkmcnt(0)
	s_barrier
	s_nop 0
	v_exp_f32_e32 v144, v144
	v_exp_f32_e32 v145, v145
	v_exp_f32_e32 v146, v146
	v_exp_f32_e32 v147, v147
	v_add_f32_e32 v210, v144, v145
	v_exp_f32_e32 v148, v148
	v_add_f32_e32 v210, v210, v146
	v_exp_f32_e32 v149, v149
	v_add_f32_e32 v210, v210, v147
	v_exp_f32_e32 v150, v150
	v_add_f32_e32 v210, v210, v148
	v_exp_f32_e32 v151, v151
	v_add_f32_e32 v210, v210, v149
	v_exp_f32_e32 v152, v152
	v_add_f32_e32 v210, v210, v150
	v_exp_f32_e32 v153, v153
	v_add_f32_e32 v210, v210, v151
	v_exp_f32_e32 v154, v154
	v_add_f32_e32 v210, v210, v152
	v_exp_f32_e32 v155, v155
	v_add_f32_e32 v210, v210, v153
	v_exp_f32_e32 v156, v156
	v_add_f32_e32 v210, v210, v154
	v_exp_f32_e32 v157, v157
	v_add_f32_e32 v210, v210, v155
	v_exp_f32_e32 v158, v158
	v_add_f32_e32 v210, v210, v156
	v_exp_f32_e32 v159, v159
	v_add_f32_e32 v210, v210, v157
	v_add_f32_e32 v210, v210, v158
	v_add_f32_e32 v210, v210, v159
	v_exp_f32_e32 v128, v128
	v_exp_f32_e32 v129, v129
	v_exp_f32_e32 v130, v130
	v_exp_f32_e32 v131, v131
	v_add_f32_e32 v211, v128, v129
	v_exp_f32_e32 v132, v132
	v_add_f32_e32 v211, v211, v130
	v_exp_f32_e32 v133, v133
	v_add_f32_e32 v211, v211, v131
	v_exp_f32_e32 v134, v134
	v_add_f32_e32 v211, v211, v132
	v_exp_f32_e32 v135, v135
	v_add_f32_e32 v211, v211, v133
	v_exp_f32_e32 v136, v136
	v_add_f32_e32 v211, v211, v134
	v_exp_f32_e32 v137, v137
	v_add_f32_e32 v211, v211, v135
	v_exp_f32_e32 v138, v138
	v_add_f32_e32 v211, v211, v136
	v_exp_f32_e32 v139, v139
	v_add_f32_e32 v211, v211, v137
	v_exp_f32_e32 v140, v140
	v_add_f32_e32 v211, v211, v138
	v_exp_f32_e32 v141, v141
	v_add_f32_e32 v211, v211, v139
	v_exp_f32_e32 v142, v142
	v_add_f32_e32 v211, v211, v140
	v_exp_f32_e32 v143, v143
	v_add_f32_e32 v211, v211, v141
	v_add_f32_e32 v211, v211, v142
	v_add_f32_e32 v211, v211, v143
	v_max_f32_e32 v212, v210, v211
	v_cmp_lt_f32_e32 vcc, 0x43800000, v212
	s_cbranch_vccnz .Lph_rare_a
.Lph_cont_a:
	v_add_f32_e32 v234, v234, v210
	v_add_f32_e32 v237, v237, v211
	v_cvt_pk_bf16_f32 v151, v150, v151
	v_cvt_pk_bf16_f32 v150, v148, v149
	v_cvt_pk_bf16_f32 v149, v146, v147
	v_cvt_pk_bf16_f32 v148, v144, v145
	v_cvt_pk_bf16_f32 v144, v152, v153
	v_cvt_pk_bf16_f32 v145, v154, v155
	v_cvt_pk_bf16_f32 v146, v156, v157
	v_cvt_pk_bf16_f32 v147, v158, v159
	v_cvt_pk_bf16_f32 v135, v134, v135
	v_cvt_pk_bf16_f32 v134, v132, v133
	v_cvt_pk_bf16_f32 v133, v130, v131
	v_cvt_pk_bf16_f32 v132, v128, v129
	v_cvt_pk_bf16_f32 v128, v136, v137
	v_cvt_pk_bf16_f32 v129, v138, v139
	v_cvt_pk_bf16_f32 v130, v140, v141
	v_cvt_pk_bf16_f32 v131, v142, v143
	s_waitcnt vmcnt(0)
	s_waitcnt lgkmcnt(0)
	s_barrier
	s_cmpk_gt_u32 s61, 0xfd
	s_cbranch_scc1 .LBB0_969
	s_add_i32 s16, s54, s64
	s_mov_b32 m0, s16
	s_nop 0
	global_load_lds_dwordx4 v218, s[20:21]
	s_add_i32 m0, s16, 0x2000
	s_nop 0
	global_load_lds_dwordx4 v218, s[18:19]
	s_and_b64 vcc, exec, s[42:43]
	s_cbranch_vccnz .LBB0_969
	s_add_i32 m0, s16, 0x4000
	s_nop 0
	global_load_lds_dwordx4 v218, s[0:1]
; #define AT_BAR() do { __builtin_amdgcn_sched_barrier(0); asm volatile("s_waitcnt lgkmcnt(0)\n\ts_barrier" ::: "memory"); __builtin_amdgcn_sched_barrier(0); } while (0)
; #define AT_VM(N) asm volatile("s_waitcnt vmcnt(" #N ")" ::: "memory")
; #define AT_PIN_M() asm volatile("" : "+v"(p[0]), "+v"(p[1]), "+v"(o[0][0]), "+v"(o[0][1]), "+v"(o[1][0]), "+v"(o[1][1]))
; __device__ __forceinline__ void attn_phase(LAS unsigned char* lds, const bf16_t* Qb, const bf16_t* Kimg, const bf16_t* Vimg, bf16_t* AB, int bid, int G, int wave_k) {
;     ...
;             AT_MSEG(b_cur, 1, b_cur, 0);
;             AT_PIN_M();
;             if (grpB) { if (issued) AT_VM(2); else AT_VM(0); }
;             AT_BAR();
;             AT_SM(false);
;             if (!grpB) { if (issued) AT_VM(3); else AT_VM(0); }
;             AT_BAR();
;             const int tmp = b_prev; b_prev = b_cur; b_cur = b_next; b_next = tmp;
;         }
.LBB0_969:
	ds_read_b128 v[136:139], v160 offset:512
	ds_read_b128 v[140:143], v160 offset:2560
	ds_read_b128 v[154:157], v160 offset:4608
	ds_read_b128 v[210:213], v160 offset:6656
	ds_read_b128 v[222:225], v160 offset:8704
	ds_read_b128 v[230:233], v160 offset:10752
	ds_read_b128 v[238:241], v160 offset:12288
	ds_read_b128 v[242:245], v160 offset:12800
	ds_read_b128 v[246:249], v160 offset:14336
	ds_read_b128 v[250:253], v160 offset:14848
	s_setprio 1
	s_waitcnt lgkmcnt(9)
	v_mfma_f32_32x32x16_bf16 v[112:127], v[136:139], v[162:165], v[64:79]
	v_mfma_f32_32x32x16_bf16 v[96:111], v[136:139], v[186:189], v[80:95]
	s_waitcnt lgkmcnt(7)
	v_mfma_f32_32x32x16_bf16 v[112:127], v[140:143], v[166:169], v[112:127]
	v_mfma_f32_32x32x16_bf16 v[96:111], v[140:143], v[190:193], v[96:111]
	v_mfma_f32_32x32x16_bf16 v[112:127], v[154:157], v[170:173], v[112:127]
	v_mfma_f32_32x32x16_bf16 v[96:111], v[154:157], v[194:197], v[96:111]
	s_waitcnt lgkmcnt(4)
	v_mfma_f32_32x32x16_bf16 v[112:127], v[210:213], v[174:177], v[112:127]
	v_mfma_f32_32x32x16_bf16 v[96:111], v[210:213], v[198:201], v[96:111]
	v_mfma_f32_32x32x16_bf16 v[112:127], v[222:225], v[178:181], v[112:127]
	v_mfma_f32_32x32x16_bf16 v[96:111], v[222:225], v[202:205], v[96:111]
	v_mfma_f32_32x32x16_bf16 v[112:127], v[230:233], v[182:185], v[112:127]
	v_mfma_f32_32x32x16_bf16 v[96:111], v[230:233], v[206:209], v[96:111]
	s_waitcnt lgkmcnt(0)
	v_mfma_f32_32x32x16_bf16 v[48:63], v[238:241], v[148:151], v[48:63]
	v_mfma_f32_32x32x16_bf16 v[32:47], v[242:245], v[148:151], v[32:47]
	v_mfma_f32_32x32x16_bf16 v[16:31], v[238:241], v[132:135], v[16:31]
	v_mfma_f32_32x32x16_bf16 v[0:15], v[242:245], v[132:135], v[0:15]
	v_mfma_f32_32x32x16_bf16 v[48:63], v[246:249], v[144:147], v[48:63]
	v_mfma_f32_32x32x16_bf16 v[32:47], v[250:253], v[144:147], v[32:47]
	v_mfma_f32_32x32x16_bf16 v[16:31], v[246:249], v[128:131], v[16:31]
	v_mfma_f32_32x32x16_bf16 v[0:15], v[250:253], v[128:131], v[0:15]
	s_setprio 0
.LBB0_974:
	s_waitcnt lgkmcnt(0)
	s_barrier
	s_nop 0
	v_exp_f32_e32 v112, v112
	v_exp_f32_e32 v113, v113
	v_exp_f32_e32 v114, v114
	v_exp_f32_e32 v115, v115
	v_add_f32_e32 v210, v112, v113
	v_exp_f32_e32 v116, v116
	v_add_f32_e32 v210, v210, v114
	v_exp_f32_e32 v117, v117
	v_add_f32_e32 v210, v210, v115
	v_exp_f32_e32 v118, v118
	v_add_f32_e32 v210, v210, v116
	v_exp_f32_e32 v119, v119
	v_add_f32_e32 v210, v210, v117
	v_exp_f32_e32 v120, v120
	v_add_f32_e32 v210, v210, v118
	v_exp_f32_e32 v121, v121
	v_add_f32_e32 v210, v210, v119
	v_exp_f32_e32 v122, v122
	v_add_f32_e32 v210, v210, v120
	v_exp_f32_e32 v123, v123
	v_add_f32_e32 v210, v210, v121
	v_exp_f32_e32 v124, v124
	v_add_f32_e32 v210, v210, v122
	v_exp_f32_e32 v125, v125
	v_add_f32_e32 v210, v210, v123
	v_exp_f32_e32 v126, v126
	v_add_f32_e32 v210, v210, v124
	v_exp_f32_e32 v127, v127
	v_add_f32_e32 v210, v210, v125
	v_add_f32_e32 v210, v210, v126
	v_add_f32_e32 v210, v210, v127
	v_exp_f32_e32 v96, v96
	v_exp_f32_e32 v97, v97
	v_exp_f32_e32 v98, v98
	v_exp_f32_e32 v99, v99
	v_add_f32_e32 v211, v96, v97
	v_exp_f32_e32 v100, v100
	v_add_f32_e32 v211, v211, v98
	v_exp_f32_e32 v101, v101
	v_add_f32_e32 v211, v211, v99
	v_exp_f32_e32 v102, v102
	v_add_f32_e32 v211, v211, v100
	v_exp_f32_e32 v103, v103
	v_add_f32_e32 v211, v211, v101
	v_exp_f32_e32 v104, v104
	v_add_f32_e32 v211, v211, v102
	v_exp_f32_e32 v105, v105
	v_add_f32_e32 v211, v211, v103
	v_exp_f32_e32 v106, v106
	v_add_f32_e32 v211, v211, v104
	v_exp_f32_e32 v107, v107
	v_add_f32_e32 v211, v211, v105
	v_exp_f32_e32 v108, v108
	v_add_f32_e32 v211, v211, v106
	v_exp_f32_e32 v109, v109
	v_add_f32_e32 v211, v211, v107
	v_exp_f32_e32 v110, v110
	v_add_f32_e32 v211, v211, v108
	v_exp_f32_e32 v111, v111
	v_add_f32_e32 v211, v211, v109
	v_add_f32_e32 v211, v211, v110
	v_add_f32_e32 v211, v211, v111
	v_max_f32_e32 v212, v210, v211
	v_cmp_lt_f32_e32 vcc, 0x43800000, v212
	s_cbranch_vccnz .Lph_rare_b
.Lph_cont_b:
	v_add_f32_e32 v234, v234, v210
	v_add_f32_e32 v237, v237, v211
	v_cvt_pk_bf16_f32 v119, v118, v119
	v_cvt_pk_bf16_f32 v118, v116, v117
	v_cvt_pk_bf16_f32 v117, v114, v115
	v_cvt_pk_bf16_f32 v116, v112, v113
	v_cvt_pk_bf16_f32 v112, v120, v121
	v_cvt_pk_bf16_f32 v113, v122, v123
	v_cvt_pk_bf16_f32 v114, v124, v125
	v_cvt_pk_bf16_f32 v115, v126, v127
	v_cvt_pk_bf16_f32 v103, v102, v103
	v_cvt_pk_bf16_f32 v102, v100, v101
	v_cvt_pk_bf16_f32 v101, v98, v99
	v_cvt_pk_bf16_f32 v100, v96, v97
	v_cvt_pk_bf16_f32 v96, v104, v105
	v_cvt_pk_bf16_f32 v97, v106, v107
	v_cvt_pk_bf16_f32 v98, v108, v109
	v_cvt_pk_bf16_f32 v99, v110, v111
.LBB0_981:
	s_waitcnt lgkmcnt(0)
	s_barrier
	s_add_i32 s61, s61, 1
	s_add_u32 s0, s0, 0x2000
	s_addc_u32 s1, s1, 0
	s_add_u32 s18, s18, s55
	s_addc_u32 s19, s19, 0
	s_add_u32 s20, s20, 0x3000
	s_addc_u32 s21, s21, 0
	s_cmpk_eq_i32 s61, 0x100
	s_cbranch_scc1 .LBB0_983
	s_mov_b32 s16, s62
	s_mov_b32 s62, s63
	s_mov_b32 s63, s64
	s_branch .LBB0_963
